# XCD-local grid syncs at sites 4,8,9,10,20 (XCD leader skips the cross-XCD level where producers and consumers share an XCD); launch-time guard: every blockIdx%8 class on exactly one XCC and 8 distinct
# speedup vs baseline: 1.0076x; 1.0076x over previous
; #define LAS __attribute__((address_space(3)))
; __device__ __forceinline__ unsigned xb_add(unsigned* p, unsigned v) { return __hip_atomic_fetch_add(p, v, __ATOMIC_RELAXED, __HIP_MEMORY_SCOPE_AGENT); }
; __device__ __forceinline__ unsigned xb_xcc_id() { return (unsigned)__builtin_amdgcn_s_getreg((3 << 11) | 20) & 0xFu; }
; #define KA_DEF const __attribute__((address_space(4))) KArgs* ka_ = (const __attribute__((address_space(4))) KArgs*)__builtin_amdgcn_kernarg_segment_ptr(); asm volatile("" : "+s"(ka_));
; __device__ __forceinline__ XcdBarrier xcd_barrier_post(unsigned* bar, volatile LAS unsigned* st) {
;     XcdBarrier b; b.bar = bar; b.x = xb_xcc_id(); b.st = st; b.tid = threadIdx.x;
;     if (threadIdx.x == 0) (void)xb_add(&bar[XB_XCNT(b.x)], 1u);
;     return b;
; }
; __global__ void __launch_bounds__(512, 2) mega_fwd(KArgs a) {
;     ...
;     volatile LAS unsigned* MISC = (volatile LAS unsigned*)(lds + 131072 + 320);
;     if (threadIdx.x < 32) MISC[threadIdx.x] = 0u;
;     __syncthreads();
;     { KA_DEF (void)xcd_barrier_post((unsigned*)WSP(WS_CTL), MISC + 8); }
_Z8mega_fwd5KArgs:
	s_load_dwordx2 s[90:91], s[0:1], 0x108
	s_load_dword s33, s[0:1], 0x110
	s_mov_b64 s[88:89], s[0:1]
	s_mov_b32 s86, s2
	s_add_u32 s2, s88, 0x108
	v_and_b32_e32 v1, 0x3ff, v0
	s_addc_u32 s3, s89, 0
	v_readfirstlane_b32 s5, v1
	v_cmp_gt_u32_e32 vcc, 32, v1
	s_and_saveexec_b64 s[0:1], vcc
	v_lshl_add_u32 v2, v1, 2, 0
	v_add_u32_e32 v2, 0x20140, v2
	v_mov_b32_e32 v3, 0
	ds_write_b32 v2, v3
	s_or_b64 exec, exec, s[0:1]
	s_mov_b64 s[6:7], s[88:89]
	s_waitcnt lgkmcnt(0)
	s_barrier
	s_getreg_b32 s10, hwreg(HW_REG_XCC_ID, 0, 4)
	s_mov_b32 s4, 0
	v_cmp_eq_u32_e32 vcc, 0, v1
	s_and_saveexec_b64 s[0:1], vcc
	s_cbranch_execz .LBB0_5
	s_mov_b64 s[8:9], exec
	v_mbcnt_lo_u32_b32 v2, s8, 0
	v_mbcnt_hi_u32_b32 v2, s9, v2
	v_cmp_eq_u32_e32 vcc, 0, v2
	s_and_b64 s[12:13], exec, vcc
	s_mov_b64 exec, s[12:13]
	s_cbranch_execz .LBB0_5
	s_load_dwordx2 s[6:7], s[6:7], 0x100
	s_lshl_b32 s10, s10, 8
	s_and_b32 s10, s10, 0xf00
	v_mov_b32_e32 v2, 0x17900000
	s_waitcnt lgkmcnt(0)
	s_lshr_b32 s11, s10, 8
	s_lshl_b32 s11, 1, s11
	v_mov_b32_e32 v3, s11
	s_and_b32 s11, s86, 7
	s_lshl_b32 s11, s11, 2
	s_add_u32 s11, s11, 0x17903800
	v_mov_b32_e32 v4, s11
	global_atomic_or v4, v3, s[6:7]
	s_add_u32 s6, s6, s10
	s_addc_u32 s7, s7, 0
	s_bcnt1_i32_b64 s8, s[8:9]
	v_mov_b32_e32 v3, s8
	global_atomic_add v2, v3, s[6:7] offset:1024

; #define KA_DEF const __attribute__((address_space(4))) KArgs* ka_ = (const __attribute__((address_space(4))) KArgs*)__builtin_amdgcn_kernarg_segment_ptr(); asm volatile("" : "+s"(ka_));
; #define MEMSSQ ((float*)WSP(WS_MEMSSQ))
; __global__ void __launch_bounds__(512, 2) mega_fwd(KArgs a) {
;     ...
;     GSYNC();
;     { KA_DEF pg8::EpiBf16S E{KVRAW, 8192, MEMSSQ}; run_gemm(TIDX, lds, MEMB, XKV, NBATCH * MEMLEN, 8192, 1024, E); }
.LBB0_1621:
	s_or_b64 exec, exec, s[0:1]
	s_mov_b64 s[0:1], s[88:89]
	s_waitcnt lgkmcnt(0)
	s_barrier
	s_load_dwordx2 s[0:1], s[0:1], 0x100
	s_movk_i32 s4, 0x800
	s_movk_i32 s5, 0x2000
	s_movk_i32 s18, 0x400
	s_waitcnt lgkmcnt(0)
	v_mov_b32_e32 v1, 0x17903800
	global_load_dwordx4 v[2:5], v1, s[0:1] sc1
	global_load_dwordx4 v[6:9], v1, s[0:1] offset:16 sc1
	s_mov_b32 vcc_lo, 0
	s_mov_b32 vcc_hi, 1
	s_waitcnt vmcnt(0)
	v_readfirstlane_b32 s2, v2
	s_nop 0
	s_or_b32 vcc_lo, vcc_lo, s2
	s_bcnt1_i32_b32 s3, s2
	s_cmp_eq_u32 s3, 1
	s_cselect_b32 vcc_hi, vcc_hi, 0
	v_readfirstlane_b32 s2, v3
	s_nop 0
	s_or_b32 vcc_lo, vcc_lo, s2
	s_bcnt1_i32_b32 s3, s2
	s_cmp_eq_u32 s3, 1
	s_cselect_b32 vcc_hi, vcc_hi, 0
	v_readfirstlane_b32 s2, v4
	s_nop 0
	s_or_b32 vcc_lo, vcc_lo, s2
	s_bcnt1_i32_b32 s3, s2
	s_cmp_eq_u32 s3, 1
	s_cselect_b32 vcc_hi, vcc_hi, 0
	v_readfirstlane_b32 s2, v5
	s_nop 0
	s_or_b32 vcc_lo, vcc_lo, s2
	s_bcnt1_i32_b32 s3, s2
	s_cmp_eq_u32 s3, 1
	s_cselect_b32 vcc_hi, vcc_hi, 0
	v_readfirstlane_b32 s2, v6
	s_nop 0
	s_or_b32 vcc_lo, vcc_lo, s2
	s_bcnt1_i32_b32 s3, s2
	s_cmp_eq_u32 s3, 1
	s_cselect_b32 vcc_hi, vcc_hi, 0
	v_readfirstlane_b32 s2, v7
	s_nop 0
	s_or_b32 vcc_lo, vcc_lo, s2
	s_bcnt1_i32_b32 s3, s2
	s_cmp_eq_u32 s3, 1
	s_cselect_b32 vcc_hi, vcc_hi, 0
	v_readfirstlane_b32 s2, v8
	s_nop 0
	s_or_b32 vcc_lo, vcc_lo, s2
	s_bcnt1_i32_b32 s3, s2
	s_cmp_eq_u32 s3, 1
	s_cselect_b32 vcc_hi, vcc_hi, 0
	v_readfirstlane_b32 s2, v9
	s_nop 0
	s_or_b32 vcc_lo, vcc_lo, s2
	s_bcnt1_i32_b32 s3, s2
	s_cmp_eq_u32 s3, 1
	s_cselect_b32 vcc_hi, vcc_hi, 0
	s_bcnt1_i32_b32 s3, vcc_lo
	s_cmp_eq_u32 s3, 8
	s_cselect_b32 vcc_hi, vcc_hi, 0
	s_nop 0
	v_writelane_b32 v254, vcc_hi, 42
	s_add_u32 s2, s0, 0x8100000
	s_addc_u32 s3, s1, 0
	s_add_u32 s6, s0, 0x3000000
	s_addc_u32 s7, s1, 0
	s_ashr_i32 s8, s4, 31
	s_lshr_b32 s8, s8, 24
	s_add_i32 s4, s4, s8
	s_ashr_i32 s28, s4, 8
	s_ashr_i32 s4, s5, 31
	s_lshr_b32 s4, s4, 24
	s_add_i32 s5, s5, s4
	s_ashr_i32 s12, s5, 8
	s_mul_i32 s4, s12, s28
	v_mov_b32_e32 v12, v220
	s_cmp_ge_i32 s86, s4
	v_readfirstlane_b32 s20, v12
	s_cbranch_scc1 .LBB0_1650
	s_ashr_i32 s5, s4, 31
	s_lshr_b32 s8, s5, 29
	s_add_i32 s8, s4, s8
	s_ashr_i32 s29, s8, 3
	s_and_b32 s8, s8, -8
	s_ashr_i32 s31, s86, 31
	s_sub_i32 s30, s4, s8
	s_lshr_b32 s8, s31, 29
	s_add_i32 s10, s86, s8
	s_and_b32 s8, s10, -8
	s_sub_i32 s11, s86, s8
	s_add_i32 s34, s29, 1
	s_cmp_ge_i32 s11, s30
	s_mul_i32 s35, s34, s30
	s_cbranch_scc0 .LBB0_1624
	s_sub_i32 s8, s11, s30
	s_mul_i32 s8, s8, s29
	s_add_i32 s13, s8, s35
	s_cbranch_execz .LBB0_1625
	s_branch .LBB0_1626
